# scan: static priority raise for the second 4-wave group
# speedup vs baseline: 1.0180x; 1.0078x over previous
; #define LAS __attribute__((address_space(3)))
; __device__ __forceinline__ unsigned pk2(float lo, float hi) { const f32x2 v = {lo, hi}; return __builtin_bit_cast(unsigned, __builtin_convertvector(v, bf16x2_t)); }
; __device__ __forceinline__ void scan2_phase(KA a, LAS unsigned char* lds, int G, const int tid, const int bid) {
;     const int wid = __builtin_amdgcn_readfirstlane(tid >> 6), lane = tid & 63, fr = lane & 15, fq = lane >> 4;
;     const int grp = wid >> 2, r = wid & 3;
;     const int mid = (r - grp) & 3;
;     unsigned char* ws = AWS;
;     const bf16_t* PROJ = (const bf16_t*)(ws + WS_PROJ); const bf16_t* LO = (const bf16_t*)AOUT; const float* KSC = (const float*)(ws + WS_SMALL) + OFF_KSC;
;     LAS unsigned char* gl0 = lds + grp * 57344;
;     const int npair = bid < 128 ? 1 : 2, pbase = bid < 128 ? bid : 128 + 2 * (bid - 128);
;     for (int pi = 0; pi < npair; ++pi) {
;         const int p = pbase + pi;
;         const int u = 2 * p + grp;
;         int row0, len, h, dir;
;         if (u < 256) { row0 = TP + (u >> 4) * 4096; len = 4096; h = (u >> 1) & 7; dir = u & 1; }
;         else { const int v = u - 256; row0 = (v >> 4) * 2048; len = 2048; h = (v >> 1) & 7; dir = v & 1; }
;         const int c = h * 64 + lane;
;         const float mpr = AIN(I_MU_PREV)[c], mnr = AIN(I_MU_NEXT)[c], mpk = AIN(I_MU_PREV)[512 + c], mnk = AIN(I_MU_NEXT)[512 + c], mpv = AIN(I_MU_PREV)[1024 + c], mnv = AIN(I_MU_NEXT)[1024 + c];
;         const float kkc = AIN(I_K_K)[c], kac = AIN(I_K_A)[c];
;         bf16_t* Y = (bf16_t*)(ws + (dir ? WS_YB : WS_YF));
;     ...
;                 for (int i = 0; i < 4; ++i) { const int s = 4 * fq + i; const bool keep = (s < fr) || (mid >= 2 && s == fr); m[i] = keep ? m[i] : 0.f; }
;                 if (mid == 0) {
; #pragma unroll
;                     for (int i = 0; i < 4; ++i) Nf[(4 * fq + i) * 20 + fr] = m[i];
;                 }
;                 else { u32x2 w; w.x = pk2(m[0], m[1]); w.y = pk2(m[2], m[3]); LAS bf16_t* dst = mid == 1 ? MkaT : (mid == 2 ? MbrT : MkrT); *(LAS u32x2*)(dst + fr * 24 + 4 * fq) = w; }
;             }
;             if (mid == 0) {
;                 float acc[16];
; #pragma unroll
;                 for (int tp = 0; tp < 16; ++tp) acc[tp] = (fr == tp) ? 1.0f : 0.f;
.LBB0_171:
	s_and_b64 vcc, exec, s[2:3]
	s_cbranch_vccz .LBB0_190
	v_readlane_b32 s14, v254, 32
	v_readlane_b32 s15, v254, 33
	s_load_dwordx4 s[4:7], s[14:15], 0x138
	v_readfirstlane_b32 s2, v134
	s_lshr_b32 s3, s2, 6
	s_ashr_i32 s33, s2, 8
	s_cmp_eq_u32 s33, 1
	s_cbranch_scc0 .Lsc_noprio
	s_setprio 1
.Lsc_noprio:
	s_sub_i32 s10, s3, s33
	s_bfe_u32 s16, s2, 0x20006
	s_and_b32 s11, s10, 3
	s_waitcnt lgkmcnt(0)
	s_add_u32 s48, s6, 0x4800000
	s_addc_u32 s49, s7, 0
	s_add_u32 s42, s6, 0x2e8000
	s_mul_i32 s2, s33, 0xe000
	s_addc_u32 s43, s7, 0
	s_add_i32 s64, s2, 0
	s_lshl_b32 s2, s73, 1
	s_add_i32 s8, s2, 0xffffff80
	s_cmpk_gt_i32 s73, 0x7f
	s_cselect_b64 s[50:51], -1, 0
	s_and_b64 s[2:3], s[50:51], exec
	s_cselect_b32 s65, s8, s73
	s_and_b32 s12, s33, 1
	s_cmp_eq_u32 s12, 0
	s_cselect_b64 s[8:9], -1, 0
	s_and_b64 s[2:3], s[8:9], exec
	s_mov_b32 s2, 0x26c00000
	s_cselect_b32 s2, s2, 0x30c00000
	s_add_u32 s2, s6, s2
	s_addc_u32 s3, s7, 0
	s_lshl_b32 s66, s16, 2
	s_not_b32 s67, s66
	s_lshl_b32 s68, s12, 9
	s_lshl_b32 s69, s16, 8
	s_cmp_eq_u32 s16, 0
	s_cselect_b64 s[6:7], -1, 0
	s_bitcmp0_b32 s10, 0
	s_cselect_b64 s[52:53], -1, 0
	s_cmp_lt_u32 s11, 2
	s_cselect_b64 s[54:55], -1, 0
	s_cmp_gt_u32 s11, 1
	s_cselect_b64 s[22:23], -1, 0
	s_cmp_lg_u32 s11, 0
	s_cselect_b64 s[56:57], -1, 0
	s_cmp_eq_u32 s11, 1
	s_cselect_b64 s[58:59], -1, 0
	s_cmp_eq_u32 s11, 2
	s_cselect_b64 s[60:61], -1, 0
	s_lshl_b32 s12, s16, 5
	s_add_u32 s2, s2, s12
	s_addc_u32 s3, s3, 0
	s_or_b32 s70, s66, 1
	s_or_b32 s71, s66, 2
	s_or_b32 s72, s66, 3
	s_waitcnt vmcnt(4)
	v_lshlrev_b32_e32 v18, 1, v76
	s_cmp_gt_u32 s16, 1
	v_lshl_add_u64 v[80:81], s[2:3], 0, v[18:19]
	s_cselect_b64 s[12:13], -1, 0
	s_cmp_eq_u32 s16, 3
	v_cmp_eq_u32_e64 s[2:3], v78, v76
	s_load_dwordx4 s[24:27], s[14:15], 0x30
	s_load_dwordx4 s[44:47], s[14:15], 0x88
	v_lshl_or_b32 v1, s16, 4, v76
	s_cselect_b64 s[14:15], -1, 0
	s_mulk_i32 s16, 0x120
	v_cmp_lt_u32_e32 vcc, v78, v76
	s_and_b64 s[2:3], s[2:3], s[22:23]
	v_add_u32_e32 v94, s16, v77
	s_or_b64 s[16:17], vcc, s[2:3]
	v_cmp_eq_u32_e64 s[2:3], v133, v76
	v_cmp_lt_u32_e32 vcc, v133, v76
	s_and_b64 s[2:3], s[2:3], s[22:23]
	s_or_b64 s[18:19], vcc, s[2:3]
	v_cmp_eq_u32_e64 s[2:3], v141, v76
	v_cmp_lt_u32_e32 vcc, v141, v76
	s_and_b64 s[2:3], s[2:3], s[22:23]
	s_or_b64 s[20:21], vcc, s[2:3]
	v_cmp_eq_u32_e64 s[2:3], v140, v76
	v_cmp_lt_u32_e32 vcc, v140, v76
	s_and_b64 s[2:3], s[2:3], s[22:23]
	s_or_b64 s[22:23], vcc, s[2:3]
	v_cmp_eq_u32_e32 vcc, 0, v76
	v_mul_u32_u24_e32 v0, 0x48, v76
	s_mov_b32 s29, 0
	v_cndmask_b32_e64 v97, 0, 1.0, vcc
	v_cmp_eq_u32_e32 vcc, 1, v76
	v_mul_u32_u24_e32 v90, 48, v76
	v_cmp_gt_u32_e64 s[10:11], 16, v77
	v_cndmask_b32_e64 v98, 0, 1.0, vcc
	v_cmp_eq_u32_e32 vcc, 2, v76
	v_mul_u32_u24_e32 v91, 48, v1
	v_mul_u32_u24_e32 v92, 24, v76
	v_cndmask_b32_e64 v99, 0, 1.0, vcc
	v_cmp_eq_u32_e32 vcc, 3, v76
	v_mul_u32_u24_e32 v93, 0x50, v76
	v_mul_u32_u24_e32 v95, 0x140, v61
	v_cndmask_b32_e64 v100, 0, 1.0, vcc
	v_cmp_eq_u32_e32 vcc, 4, v76
	v_mul_u32_u24_e32 v96, 0x50, v133
	v_mul_u32_u24_e32 v113, 44, v77
	v_cndmask_b32_e64 v101, 0, 1.0, vcc
	v_cmp_eq_u32_e32 vcc, 5, v76
	v_mul_i32_i24_e32 v114, 0xffffffd4, v77
	v_mul_i32_i24_e32 v115, 0xffffffa0, v76
	v_cndmask_b32_e64 v102, 0, 1.0, vcc
	v_cmp_eq_u32_e32 vcc, 6, v76
	s_sub_i32 s75, 0, s66
	v_not_b32_e32 v116, v78
	v_cndmask_b32_e64 v103, 0, 1.0, vcc
	v_cmp_eq_u32_e32 vcc, 7, v76
	s_mov_b64 s[2:3], -1
	v_lshlrev_b32_e32 v117, 1, v0
	v_cndmask_b32_e64 v104, 0, 1.0, vcc
	v_cmp_eq_u32_e32 vcc, 8, v76
	s_nop 1
	v_cndmask_b32_e64 v105, 0, 1.0, vcc
	v_cmp_eq_u32_e32 vcc, 9, v76
	s_nop 1
	v_cndmask_b32_e64 v106, 0, 1.0, vcc
	v_cmp_eq_u32_e32 vcc, 10, v76
	s_nop 1
	v_cndmask_b32_e64 v107, 0, 1.0, vcc
	v_cmp_eq_u32_e32 vcc, 11, v76
	s_nop 1
	v_cndmask_b32_e64 v108, 0, 1.0, vcc
	v_cmp_eq_u32_e32 vcc, 12, v76
	s_nop 1
	v_cndmask_b32_e64 v109, 0, 1.0, vcc
	v_cmp_eq_u32_e32 vcc, 13, v76
	s_nop 1
	v_cndmask_b32_e64 v110, 0, 1.0, vcc
	v_cmp_eq_u32_e32 vcc, 14, v76
	s_nop 1
	v_cndmask_b32_e64 v111, 0, 1.0, vcc
	v_cmp_eq_u32_e32 vcc, 15, v76
	s_nop 1
	v_cndmask_b32_e64 v112, 0, 1.0, vcc
	s_branch .LBB0_174

; __global__ void __launch_bounds__(512, 2) fwd_kernel(Args args_unused) {
;     ...
;         case 4: if (EN(4)) { if (SCAN_V == 1) scan_phase(a, lds, G, tid, bid); else if (bid < 160) scan2_phase(a, lds, G, tid, bid); else gla_phase(a, lds, G, tid, bid); }
.LBB0_190:
	s_setprio 0
	s_mov_b64 s[12:13], 0
